# rowpass A: xor-1/2/4/8 steps of the two per-row wave reductions use DPP adds instead of ds_bpermute round trips (bitwise-identical sums)
# speedup vs baseline: 1.0034x; 1.0034x over previous
.LBB0_390:
	s_and_b32 s0, s14, 0x7ff
	s_cmpk_lt_i32 s14, 0x4000
	s_cselect_b32 s0, s0, s17
	v_lshl_or_b32 v152, s0, 9, v8
	v_lshl_add_u64 v[120:121], s[6:7], 0, v[152:153]
	global_load_dwordx2 v[100:101], v[120:121], off
	v_lshl_add_u64 v[118:119], s[8:9], 0, v[16:17]
	v_add_co_u32_e32 v118, vcc, 0xc701000, v118
	s_nop 1
	v_addc_co_u32_e32 v119, vcc, 0, v119, vcc
	global_load_ushort v102, v[118:119], off
	global_load_ushort v103, v[118:119], off offset:128
	global_load_ushort v104, v[118:119], off offset:256
	global_load_ushort v105, v[118:119], off offset:384
	global_load_ushort v106, v[118:119], off offset:512
	global_load_ushort v107, v[118:119], off offset:640
	global_load_ushort v108, v[118:119], off offset:768
	global_load_ushort v109, v[118:119], off offset:896
	global_load_ushort v110, v[118:119], off offset:1024
	global_load_ushort v111, v[118:119], off offset:1152
	global_load_ushort v112, v[118:119], off offset:1280
	global_load_ushort v113, v[118:119], off offset:1408
	global_load_ushort v114, v[118:119], off offset:1536
	global_load_ushort v115, v[118:119], off offset:1664
	global_load_ushort v116, v[118:119], off offset:1792
	global_load_ushort v117, v[118:119], off offset:1920
	v_lshl_add_u64 v[18:19], s[8:9], 0, v[14:15]
	v_add_co_u32_e32 v44, vcc, 0xc700000, v18
	s_cmpk_gt_i32 s14, 0x3fff
	s_nop 0
	v_addc_co_u32_e32 v45, vcc, 0, v19, vcc
	flat_load_dwordx4 v[0:3], v[44:45] offset:3072
	flat_load_dwordx4 v[4:7], v[44:45] offset:2048
	s_cselect_b64 s[10:11], -1, 0
	s_add_i32 s0, s14, 0xffffc000
	s_lshl_b64 s[4:5], s[0:1], 12
	s_add_u32 s12, s15, s4
	s_addc_u32 s13, s16, s5
	s_cmpk_lt_i32 s14, 0x4000
	v_lshlrev_b32_e32 v152, 2, v8
	s_waitcnt vmcnt(0) lgkmcnt(0)
	v_lshlrev_b32_e32 v20, 16, v0
	v_lshlrev_b32_e32 v50, 16, v4
	v_and_b32_e32 v21, 0xffff0000, v0
	v_and_b32_e32 v51, 0xffff0000, v4
	v_add_f32_e32 v0, 0, v50
	v_lshlrev_b32_e32 v46, 16, v5
	v_add_f32_e32 v0, v0, v51
	v_and_b32_e32 v47, 0xffff0000, v5
	v_add_f32_e32 v0, v0, v46
	v_lshlrev_b32_e32 v48, 16, v6
	v_add_f32_e32 v0, v0, v47
	v_and_b32_e32 v49, 0xffff0000, v6
	v_add_f32_e32 v0, v0, v48
	v_lshlrev_b32_e32 v28, 16, v7
	v_add_f32_e32 v0, v0, v49
	v_and_b32_e32 v29, 0xffff0000, v7
	v_add_f32_e32 v0, v0, v28
	v_add_f32_e32 v0, v0, v29
	v_add_f32_e32 v0, v0, v20
	v_lshlrev_b32_e32 v22, 16, v1
	v_add_f32_e32 v0, v0, v21
	v_and_b32_e32 v23, 0xffff0000, v1
	v_add_f32_e32 v0, v0, v22
	v_lshlrev_b32_e32 v24, 16, v2
	v_add_f32_e32 v0, v0, v23
	v_and_b32_e32 v25, 0xffff0000, v2
	v_add_f32_e32 v0, v0, v24
	v_lshlrev_b32_e32 v26, 16, v3
	v_add_f32_e32 v0, v0, v25
	v_and_b32_e32 v27, 0xffff0000, v3
	v_add_f32_e32 v0, v0, v26
	v_add_f32_e32 v0, v0, v27
	s_nop 1
	v_add_f32_dpp v0, v0, v0 quad_perm:[1,0,3,2] row_mask:0xf bank_mask:0xf
	s_nop 1
	v_add_f32_dpp v0, v0, v0 quad_perm:[2,3,0,1] row_mask:0xf bank_mask:0xf
	s_nop 1
	v_add_f32_dpp v0, v0, v0 row_half_mirror row_mask:0xf bank_mask:0xf
	s_nop 1
	v_add_f32_dpp v0, v0, v0 row_mirror row_mask:0xf bank_mask:0xf
	ds_bpermute_b32 v1, v33, v0
	s_waitcnt lgkmcnt(0)
	v_add_f32_e32 v35, v0, v1
	ds_bpermute_b32 v52, v34, v35
	v_mov_b32_e32 v0, v68
	v_mov_b32_e32 v1, v69
	v_mov_b32_e32 v2, v70
	v_mov_b32_e32 v3, v71
	v_mov_b32_e32 v36, v72
	v_mov_b32_e32 v37, v73
	v_mov_b32_e32 v38, v74
	v_mov_b32_e32 v39, v75
	v_mov_b32_e32 v4, v76
	v_mov_b32_e32 v5, v77
	v_mov_b32_e32 v6, v78
	v_mov_b32_e32 v7, v79
	v_mov_b32_e32 v40, v80
	v_mov_b32_e32 v41, v81
	v_mov_b32_e32 v42, v82
	v_mov_b32_e32 v43, v83
	s_waitcnt lgkmcnt(0)
	v_add_f32_e32 v35, v35, v52
	v_mul_f32_e32 v52, 0x3a800000, v35
	v_pk_add_f32 v[50:51], v[50:51], v[52:53] op_sel_hi:[1,0] neg_lo:[0,1] neg_hi:[0,1]
	v_pk_add_f32 v[46:47], v[46:47], v[52:53] op_sel_hi:[1,0] neg_lo:[0,1] neg_hi:[0,1]
	v_pk_add_f32 v[54:55], v[28:29], v[52:53] op_sel_hi:[1,0] neg_lo:[0,1] neg_hi:[0,1]
	v_pk_mul_f32 v[28:29], v[50:51], v[50:51]
	v_pk_add_f32 v[48:49], v[48:49], v[52:53] op_sel_hi:[1,0] neg_lo:[0,1] neg_hi:[0,1]
	v_pk_add_f32 v[20:21], v[20:21], v[52:53] op_sel_hi:[1,0] neg_lo:[0,1] neg_hi:[0,1]
	v_pk_add_f32 v[22:23], v[22:23], v[52:53] op_sel_hi:[1,0] neg_lo:[0,1] neg_hi:[0,1]
	v_pk_add_f32 v[24:25], v[24:25], v[52:53] op_sel_hi:[1,0] neg_lo:[0,1] neg_hi:[0,1]
	v_pk_add_f32 v[26:27], v[26:27], v[52:53] op_sel_hi:[1,0] neg_lo:[0,1] neg_hi:[0,1]
	v_pk_mul_f32 v[52:53], v[46:47], v[46:47]
	v_add_f32_e32 v28, v28, v29
	v_add_f32_e32 v28, v52, v28
	v_pk_mul_f32 v[56:57], v[48:49], v[48:49]
	v_add_f32_e32 v28, v53, v28
	v_add_f32_e32 v28, v56, v28
	v_pk_mul_f32 v[58:59], v[54:55], v[54:55]
	v_add_f32_e32 v28, v57, v28
	v_add_f32_e32 v28, v58, v28
	v_pk_mul_f32 v[60:61], v[20:21], v[20:21]
	v_add_f32_e32 v28, v59, v28
	v_add_f32_e32 v28, v60, v28
	v_pk_mul_f32 v[62:63], v[22:23], v[22:23]
	v_add_f32_e32 v28, v61, v28
	v_add_f32_e32 v28, v62, v28
	v_pk_mul_f32 v[64:65], v[24:25], v[24:25]
	v_add_f32_e32 v28, v63, v28
	v_add_f32_e32 v28, v64, v28
	v_pk_mul_f32 v[66:67], v[26:27], v[26:27]
	v_add_f32_e32 v28, v65, v28
	v_add_f32_e32 v28, v66, v28
	v_add_f32_e32 v28, v67, v28
	s_nop 1
	v_add_f32_dpp v28, v28, v28 quad_perm:[1,0,3,2] row_mask:0xf bank_mask:0xf
	s_nop 1
	v_add_f32_dpp v28, v28, v28 quad_perm:[2,3,0,1] row_mask:0xf bank_mask:0xf
	s_nop 1
	v_add_f32_dpp v28, v28, v28 row_half_mirror row_mask:0xf bank_mask:0xf
	s_nop 1
	v_add_f32_dpp v28, v28, v28 row_mirror row_mask:0xf bank_mask:0xf
	ds_bpermute_b32 v29, v33, v28
	s_waitcnt lgkmcnt(0)
	v_add_f32_e32 v28, v28, v29
	ds_bpermute_b32 v29, v34, v28
	s_waitcnt lgkmcnt(0)
	v_add_f32_e32 v28, v28, v29
	v_fmamk_f32 v28, v28, 0x3a800000, v183
	v_mul_f32_e32 v29, 0x4f800000, v28
	v_cmp_gt_f32_e32 vcc, s87, v28
	s_nop 1
	v_cndmask_b32_e32 v28, v28, v29, vcc
	v_sqrt_f32_e32 v29, v28
	s_nop 0
	v_add_u32_e32 v35, -1, v29
	v_add_u32_e32 v52, 1, v29
	v_fma_f32 v53, -v35, v29, v28
	v_fma_f32 v56, -v52, v29, v28
	v_cmp_ge_f32_e64 s[4:5], 0, v53
	s_nop 1
	v_cndmask_b32_e64 v29, v29, v35, s[4:5]
	v_cmp_lt_f32_e64 s[4:5], 0, v56
	s_nop 1
	v_cndmask_b32_e64 v29, v29, v52, s[4:5]
	v_mul_f32_e32 v35, 0x37800000, v29
	v_cndmask_b32_e32 v29, v29, v35, vcc
	v_cmp_class_f32_e32 vcc, v28, v189
	s_nop 1
	v_cndmask_b32_e32 v28, v29, v28, vcc
	v_div_scale_f32 v29, s[4:5], v28, v28, 1.0
	v_rcp_f32_e32 v35, v29
	v_div_scale_f32 v52, vcc, 1.0, v28, 1.0
	v_fma_f32 v53, -v29, v35, 1.0
	v_fmac_f32_e32 v35, v53, v35
	v_mul_f32_e32 v53, v52, v35
	v_fma_f32 v56, -v29, v53, v52
	v_fmac_f32_e32 v53, v56, v35
	v_fma_f32 v29, -v29, v53, v52
	v_div_fmas_f32 v29, v29, v35, v53
	v_div_fixup_f32 v28, v29, v28, 1.0
	v_pk_mul_f32 v[50:51], v[50:51], v[28:29] op_sel_hi:[1,0]
	v_pk_mul_f32 v[48:49], v[48:49], v[28:29] op_sel_hi:[1,0]
	v_pk_mul_f32 v[46:47], v[46:47], v[28:29] op_sel_hi:[1,0]
	v_pk_mul_f32 v[52:53], v[54:55], v[28:29] op_sel_hi:[1,0]
	v_pk_fma_f32 v[4:5], v[0:1], v[50:51], v[4:5]
	v_pk_fma_f32 v[0:1], v[36:37], v[48:49], v[40:41]
	v_pk_fma_f32 v[6:7], v[2:3], v[46:47], v[6:7]
	v_pk_fma_f32 v[2:3], v[38:39], v[52:53], v[42:43]
	v_cvt_pk_bf16_f32 v36, v4, v5
	v_cvt_pk_bf16_f32 v37, v6, v7
	v_cvt_pk_bf16_f32 v38, v0, v1
	v_cvt_pk_bf16_f32 v39, v2, v3
	flat_store_dwordx4 v[44:45], v[36:39] offset:2048
	s_cbranch_scc1 .LBB0_392
	s_nop 0
	v_lshl_add_u64 v[36:37], s[12:13], 0, v[152:153]
	flat_store_dwordx4 v[36:37], v[4:7] nt
	flat_store_dwordx4 v[36:37], v[0:3] offset:16 nt
